# experiment: one static s_setprio 1 for waves 4-7 at kernel entry (no other priority changes)
# baseline (speedup 1.0000x reference)
; #define LAS __attribute__((address_space(3)))
; __device__ __forceinline__ unsigned xb_add(unsigned* p, unsigned v) { return __hip_atomic_fetch_add(p, v, __ATOMIC_RELAXED, __HIP_MEMORY_SCOPE_AGENT); }
; __device__ __forceinline__ unsigned xb_xcc_id() { return (unsigned)__builtin_amdgcn_s_getreg((3 << 11) | 20) & 0xFu; }
; __global__ void __launch_bounds__(512, 2) fwd_megakernel(Params Parg) {
;     extern __shared__ __attribute__((aligned(16))) unsigned char shm[];
;     LAS unsigned char* lds = (LAS unsigned char*)shm;
;     cg::grid_group grid = cg::this_grid();
;     if (threadIdx.x < 4) ((volatile LAS unsigned*)(lds + LDS_BAR_OFF))[threadIdx.x] = 0u;
;     __syncthreads();
;     { KParams _p = (KParams)__builtin_amdgcn_kernarg_segment_ptr(); if (threadIdx.x == 0) (void)xb_add(&((unsigned*)(_p->ws + WS_BAR))[XB_XCNT(xb_xcc_id())], 1u); }
_Z14fwd_megakernel6Params:
	s_load_dwordx2 s[28:29], s[0:1], 0xd8
	s_load_dword s13, s[0:1], 0xe0
	s_add_u32 s14, s0, 0xd8
	v_and_b32_e32 v176, 0x3ff, v0
	s_addc_u32 s15, s1, 0
	v_readfirstlane_b32 s98, v176
	s_nop 3
	s_lshr_b32 s98, s98, 6
	s_cmp_ge_u32 s98, 4
	s_cbranch_scc0 .Lprio_skip
	s_setprio 1
.Lprio_skip:
	v_cmp_gt_u32_e32 vcc, 4, v176
	s_and_saveexec_b64 s[4:5], vcc
	v_lshl_add_u32 v1, v176, 2, 0
	v_add_u32_e32 v1, 0x23000, v1
	v_mov_b32_e32 v2, 0
	ds_write_b32 v1, v2
	s_or_b64 exec, exec, s[4:5]
	s_waitcnt lgkmcnt(0)
	s_barrier
	v_cmp_eq_u32_e64 s[4:5], 0, v176
	s_mov_b64 s[6:7], exec
	s_nop 0
	v_writelane_b32 v254, s4, 0
	s_nop 1
	v_writelane_b32 v254, s5, 1
	s_and_b64 s[4:5], s[6:7], s[4:5]
	s_mov_b64 exec, s[4:5]
	s_cbranch_execz .LBB0_5
	s_mov_b64 s[8:9], exec
	v_mbcnt_lo_u32_b32 v1, s8, 0
	v_mbcnt_hi_u32_b32 v1, s9, v1
	v_cmp_eq_u32_e32 vcc, 0, v1
	s_getreg_b32 s3, hwreg(HW_REG_XCC_ID, 0, 4)
	s_and_b64 s[4:5], exec, vcc
	s_mov_b64 exec, s[4:5]
	s_cbranch_execz .LBB0_5
	s_load_dwordx2 s[4:5], s[0:1], 0xd0
	s_lshl_b32 s3, s3, 8
	s_and_b32 s3, s3, 0xf00
	v_mov_b32_e32 v1, 0x4700000
	s_waitcnt lgkmcnt(0)
	s_add_u32 s4, s4, s3
	s_addc_u32 s5, s5, 0
	s_bcnt1_i32_b64 s3, s[8:9]
	v_mov_b32_e32 v2, s3
	global_atomic_add v1, v2, s[4:5] offset:1024
